# attention item order: each XCD covers 8 heads x 4 adjacent query-block pairs (L2 channel spreading), paired re-evaluation
# baseline (speedup 1.0000x reference)
; #define LAS __attribute__((address_space(3)))
; __device__ __forceinline__ void attn_block(LAS unsigned char* lds, const bf16_t* P, bf16_t* mix, int b, int h, int qb, float lam, float outscale, const float* subln) {
;     int tid_ = threadIdx.x; asm volatile("" : "+v"(tid_));
;     const int tid = tid_, lane = tid & 63, wave = __builtin_amdgcn_readfirstlane(tid >> 6), r32 = lane & 31, hi = lane >> 5;
;     const int comp = wave >> 2, wq = wave & 3;
;     const int rb = b * SEQ, q0 = qb * 128, qw0 = q0 + wq * 32, qrow = qw0 + r32;
;     const float C1 = 0.125f * 1.4426950408889634f;
;     bf16x8 qf[4];
;     { const bf16_t* qp = P + (size_t)(rb + qrow) * INC + COL_AQ + h * 128 + comp * 64 + hi * 8;
; #pragma unroll
;       for (int ks = 0; ks < 4; ++ks) qf[ks] = *(const bf16x8*)(qp + 16 * ks); }
;     const int ntiles = 2 * qb + 2;
;     const int srow = tid >> 4, sch = tid & 15;
;     const bf16_t* kg = P + (size_t)rb * INC + COL_AK + h * 128 + sch * 8;
;     const bf16_t* vg = P + (size_t)rb * INC + COL_AV + h * 128 + sch * 8;
;     const unsigned so0 = off_b(srow, sch), so1 = off_b(srow + 32, sch);
;     u32x4 kr0, kr1, vr0, vr1;
;     kr0 = *(const u32x4*)(kg + (size_t)srow * INC); kr1 = *(const u32x4*)(kg + (size_t)(srow + 32) * INC);
;     vr0 = *(const u32x4*)(vg + (size_t)srow * INC); vr1 = *(const u32x4*)(vg + (size_t)(srow + 32) * INC);
;     *(LAS u32x4*)(lds + ATT_K0 + so0) = kr0; *(LAS u32x4*)(lds + ATT_K0 + so1) = kr1;
;     *(LAS u32x4*)(lds + ATT_V0 + so0) = vr0; *(LAS u32x4*)(lds + ATT_V0 + so1) = vr1;
; __device__ __forceinline__ void attn_phase(LAS unsigned char* lds, const Params& p, int layer) {
;     ...
;     for (int it0 = bid; it0 < 512; it0 += nblk) {
;         int it = it0;
;         if (nblk == 256) { const int x = bid & 7, j = bid >> 3, r = it0 >> 8; it = (2 * x + r) * 32 + j; }
;         const int bh = it >> 5, pr = it & 31, b = bh >> 3, h = bh & 7;
;         attn_block(lds, P, mix, b, h, pr, lam, 1.0f - lambda_init, subln);
.LBB0_98:
	s_and_b32 s2, s66, 4
	s_lshl_b32 s2, s2, 6
	s_and_b32 s72, s66, 0x38
	s_lshl_b32 s72, s72, 2
	s_or_b32 s2, s2, s72
	s_and_b32 s72, s66, 3
	s_lshl_b32 s72, s72, 3
	s_or_b32 s2, s2, s72
	s_lshr_b32 s72, s66, 6
	s_and_b32 s72, s72, 7
	s_or_b32 s2, s2, s72
	s_and_b64 s[38:39], s[46:47], exec
	v_mov_b32_e32 v20, v212
	s_cselect_b32 s72, s2, s66
	s_and_b32 s33, s72, 31
	v_readfirstlane_b32 s42, v20
	s_lshr_b32 s36, s42, 1
	s_lshl_b32 s73, s33, 7
	s_and_b32 s60, s36, 0x60
	v_and_b32_e32 v166, 31, v20
	s_lshl_b32 s2, s72, 5
	s_or_b32 s61, s73, s60
	v_readlane_b32 s52, v255, 12
	s_and_b32 s2, s2, 0xffffe000
	v_or_b32_e32 v176, s61, v166
	v_readlane_b32 s53, v255, 13
	v_or_b32_e32 v130, s2, v176
	s_movk_i32 s74, 0x3800
	v_mov_b64_e32 v[2:3], s[52:53]
	v_mad_i64_i32 v[2:3], s[38:39], v130, s74, v[2:3]
	s_lshl_b32 s36, s72, 2
	s_ashr_i32 s43, s42, 8
	s_and_b32 s38, s36, 0x380
	s_lshl_b32 s36, s38, 1
	s_lshl_b32 s50, s43, 6
	v_lshl_add_u64 v[2:3], v[2:3], 0, s[36:37]
	s_ashr_i32 s51, s50, 31
	v_lshl_add_u64 v[2:3], s[50:51], 1, v[2:3]
	s_mul_i32 s50, s2, 0x3800
	s_mul_hi_i32 s51, s2, 0x3800
	s_add_u32 s39, s52, s50
	v_bfe_u32 v165, v20, 5, 1
	s_addc_u32 s63, s53, s51
	v_lshlrev_b32_e32 v0, 4, v165
	v_and_b32_e32 v22, 15, v20
	s_add_u32 s62, s39, s36
	v_lshl_add_u64 v[18:19], v[2:3], 0, v[0:1]
	v_ashrrev_i32_e32 v21, 4, v20
	s_addc_u32 s63, s63, 0
	v_lshlrev_b32_e32 v0, 4, v22
	v_lshl_add_u64 v[2:3], s[62:63], 0, v[0:1]
	v_add_u32_e32 v23, 32, v21
	v_mad_i64_i32 v[4:5], s[70:71], v21, s74, v[2:3]
	v_mad_i64_i32 v[6:7], s[70:71], v23, s74, v[2:3]
	s_add_u32 s64, s62, 0x1000
	global_load_dwordx4 v[2:5], v[4:5], off offset:2048
	s_nop 0
	global_load_dwordx4 v[6:9], v[6:7], off offset:2048
	s_addc_u32 s65, s63, 0
	v_lshl_add_u64 v[10:11], s[64:65], 0, v[0:1]
	v_mad_i64_i32 v[12:13], s[70:71], v21, s74, v[10:11]
	v_mad_i64_i32 v[14:15], s[70:71], v23, s74, v[10:11]
	global_load_dwordx4 v[10:13], v[12:13], off
	s_nop 0
	global_load_dwordx4 v[14:17], v[14:15], off
	s_nop 0
	global_load_dwordx4 v[110:113], v[18:19], off
	global_load_dwordx4 v[106:109], v[18:19], off offset:32
	global_load_dwordx4 v[102:105], v[18:19], off offset:64
	global_load_dwordx4 v[98:101], v[18:19], off offset:96
	v_lshlrev_b32_e32 v26, 2, v21
	v_bfe_u32 v27, v21, 2, 2
	v_and_b32_e32 v26, 12, v26
	v_lshlrev_b32_e32 v29, 8, v23
	v_lshlrev_b32_e32 v23, 2, v23
	v_lshlrev_b32_e32 v25, 8, v21
	v_bitop3_b32 v26, v26, v22, v27 bitop3:0x36
	v_and_b32_e32 v23, 12, v23
	v_lshl_or_b32 v179, v26, 4, v25
	v_bitop3_b32 v22, v23, v22, v27 bitop3:0x36
	v_lshl_or_b32 v182, v22, 4, v29
	v_add_u32_e32 v22, 0, v179
	v_bfe_u32 v19, v20, 2, 2
	v_lshrrev_b32_e32 v24, 3, v20
	v_add_u32_e32 v23, 0, v182
	v_lshlrev_b32_e32 v164, 2, v165
	v_lshlrev_b32_e32 v18, 2, v20
	v_and_or_b32 v18, v18, 12, v19
	s_lshl_b32 s36, s43, 3
	s_lshl_b32 s39, s72, 3
	v_lshlrev_b32_e32 v28, 8, v166
	v_or_b32_e32 v25, s36, v165
	v_bitop3_b32 v26, s36, v18, v165 bitop3:0x36
	s_and_b32 s39, s39, 0x700
	v_lshl_add_u32 v180, v26, 4, v28
	v_bitop3_b32 v26, v25, v18, 2 bitop3:0x36
	v_bitop3_b32 v27, v25, v18, 4 bitop3:0x36
	v_bitop3_b32 v18, v25, v18, 6 bitop3:0x36
	v_lshl_add_u32 v181, v26, 4, v28
	v_lshl_add_u32 v178, v27, 4, v28
	v_lshl_add_u32 v177, v18, 4, v28
	v_lshlrev_b32_e32 v132, 3, v165
	v_ashrrev_i32_e32 v131, 31, v130
	s_or_b32 s69, s61, 31
	s_or_b32 s36, s73, 64
	v_mov_b32_e32 v175, 0xff800000
	v_mov_b32_e32 v167, 0
	s_waitcnt vmcnt(7)
	ds_write_b128 v22, v[2:5]
	s_waitcnt vmcnt(6)
	ds_write_b128 v23, v[6:9]
	s_waitcnt vmcnt(5)
	ds_write_b128 v22, v[10:13] offset:32768
	s_waitcnt vmcnt(4)
; __device__ __forceinline__ void attn_block(LAS unsigned char* lds, const bf16_t* P, bf16_t* mix, int b, int h, int qb, float lam, float outscale, const float* subln) {
;     ...
;     float mrun = -INFINITY, lrun = 0.f;
;     f32x16 o[4];
; #pragma unroll
;     for (int c = 0; c < 4; ++c)
; #pragma unroll
;         for (int j = 0; j < 16; ++j) o[c][j] = 0.f;
;     const int blk = (lane >> 4) & 1, qq = (lane & 15) >> 2, pp = lane & 3;
;     unsigned kbase[4], vbase[4][2];
; #pragma unroll
;     for (int ks = 0; ks < 4; ++ks) kbase[ks] = off_b(r32, comp * 8 + 2 * ks + hi);
; #pragma unroll
;     for (int c = 0; c < 4; ++c)
; #pragma unroll
;         for (int t = 0; t < 2; ++t) vbase[c][t] = off_b(8 * t + 4 * hi + qq, 4 * c + 2 * blk + (pp >> 1)) + 8 * (pp & 1);
;     asm volatile("" :: "v"(qf[0]), "v"(qf[1]), "v"(qf[2]), "v"(qf[3]));
;     for (int kt = 0; kt < ntiles; ++kt) {
	ds_write_b128 v23, v[14:17] offset:32768
	v_bfe_u32 v2, v20, 1, 1
	v_and_or_b32 v2, v24, 2, v2
	v_lshlrev_b32_e32 v3, 2, v19
	v_lshlrev_b32_e32 v4, 3, v20
	v_or_b32_e32 v5, v164, v19
	v_bitop3_b32 v6, v3, v2, v165 bitop3:0x36
	v_and_b32_e32 v4, 8, v4
	v_lshlrev_b32_e32 v5, 8, v5
	v_lshlrev_b32_e32 v6, 4, v6
	v_or3_b32 v173, v6, v5, v4
	v_or_b32_e32 v6, 8, v164
	v_or_b32_e32 v7, v6, v19
	v_lshrrev_b32_e32 v6, 2, v6
	v_lshlrev_b32_e32 v7, 8, v7
	v_bitop3_b32 v8, v6, v2, v3 bitop3:0x36
	v_lshl_add_u32 v8, v8, 4, v7
	v_or_b32_e32 v174, v8, v4
	v_or_b32_e32 v8, 4, v2
	v_bitop3_b32 v9, v3, v8, v165 bitop3:0x36
	v_bitop3_b32 v8, v6, v8, v3 bitop3:0x36
	v_lshl_add_u32 v8, v8, 4, v7
	v_lshlrev_b32_e32 v9, 4, v9
	v_or_b32_e32 v172, v8, v4
	v_or_b32_e32 v8, 8, v2
	v_or3_b32 v170, v9, v5, v4
	v_bitop3_b32 v9, v3, v8, v165 bitop3:0x36
	v_bitop3_b32 v8, v6, v8, v3 bitop3:0x36
	v_lshl_add_u32 v8, v8, 4, v7
	v_or_b32_e32 v2, 12, v2
	v_or_b32_e32 v171, v8, v4
	v_bitop3_b32 v8, v3, v2, v165 bitop3:0x36
	v_bitop3_b32 v2, v6, v2, v3 bitop3:0x36
	v_lshl_add_u32 v2, v2, 4, v7
	v_or_b32_e32 v169, v2, v4
	v_mov_b64_e32 v[2:3], s[50:51]
	v_mad_i64_i32 v[2:3], s[70:71], v21, s74, v[2:3]
	v_lshlrev_b32_e32 v9, 4, v9
	v_lshlrev_b32_e32 v8, 4, v8
	v_or3_b32 v2, v2, s39, v0
	v_mov_b32_e32 v14, v1
	v_mov_b32_e32 v15, v1
	v_or3_b32 v168, v9, v5, v4
	v_or3_b32 v145, v8, v5, v4
	v_lshl_add_u64 v[134:135], s[48:49], 0, v[2:3]
	v_mov_b32_e32 v0, v1
	v_mov_b32_e32 v2, v1
	v_mov_b32_e32 v3, v1
	v_mov_b32_e32 v4, v1
	v_mov_b32_e32 v5, v1
	v_mov_b32_e32 v6, v1
	v_mov_b32_e32 v7, v1
	v_mov_b32_e32 v8, v1
	v_mov_b32_e32 v9, v1
	v_mov_b32_e32 v10, v1
	v_mov_b32_e32 v11, v1
	v_mov_b32_e32 v12, v1
	v_mov_b32_e32 v13, v1
	v_mov_b64_e32 v[64:65], v[14:15]
	v_mov_b64_e32 v[48:49], v[14:15]
	v_mov_b64_e32 v[32:33], v[14:15]
	v_mov_b64_e32 v[62:63], v[12:13]
	v_mov_b64_e32 v[60:61], v[10:11]
	v_mov_b64_e32 v[58:59], v[8:9]
	v_mov_b64_e32 v[56:57], v[6:7]
	v_mov_b64_e32 v[54:55], v[4:5]
	v_mov_b64_e32 v[52:53], v[2:3]
	v_mov_b64_e32 v[50:51], v[0:1]
	v_mov_b64_e32 v[46:47], v[12:13]
	v_mov_b64_e32 v[44:45], v[10:11]
	v_mov_b64_e32 v[42:43], v[8:9]
	v_mov_b64_e32 v[40:41], v[6:7]
	v_mov_b64_e32 v[38:39], v[4:5]
	v_mov_b64_e32 v[36:37], v[2:3]
	v_mov_b64_e32 v[34:35], v[0:1]
	v_mov_b64_e32 v[30:31], v[12:13]
	v_mov_b64_e32 v[28:29], v[10:11]
	v_mov_b64_e32 v[26:27], v[8:9]
	v_mov_b64_e32 v[24:25], v[6:7]
	v_mov_b64_e32 v[22:23], v[4:5]
	v_mov_b64_e32 v[20:21], v[2:3]
	v_mov_b64_e32 v[18:19], v[0:1]
	v_mov_b64_e32 v[16:17], v[14:15]
	s_mov_b32 s70, 0
	s_mov_b32 s71, 0
	v_mov_b64_e32 v[14:15], v[12:13]
	v_mov_b64_e32 v[12:13], v[10:11]
	v_mov_b64_e32 v[10:11], v[8:9]
	v_mov_b64_e32 v[8:9], v[6:7]
	v_mov_b64_e32 v[6:7], v[4:5]
	v_mov_b64_e32 v[4:5], v[2:3]
	v_mov_b64_e32 v[2:3], v[0:1]
	s_waitcnt vmcnt(0)
	v_lshrrev_b32_e32 v0, 4, v212
	v_and_b32_e32 v203, 3, v0
	v_lshlrev_b32_e32 v203, 2, v203
	v_bfe_u32 v0, v0, 2, 2
	v_or_b32_e32 v0, v203, v0
	v_lshlrev_b32_e32 v0, 4, v0
	v_xor_b32_e32 v134, v134, v0
	s_nop 0
	v_add_co_u32_e32 v200, vcc, 0x70000, v134
	s_nop 1
	v_addc_co_u32_e32 v201, vcc, 0, v135, vcc
	s_nop 0
	s_movk_i32 s73, 0x4000
	s_lshl_b32 s70, s42, 4
	s_and_b32 s70, s70, 0x1c00
	s_add_i32 s73, s73, s70
	s_add_i32 m0, s73, 0x0
	s_nop 0
	global_load_lds_dwordx4 v[134:135], off
	s_add_i32 m0, s73, 0x2000
	s_nop 0
	global_load_lds_dwordx4 v[200:201], off
	s_add_i32 m0, s73, 0x7800
	s_nop 0
	global_load_lds_dwordx4 v[134:135], off offset:2048
	s_add_i32 m0, s73, 0x9800
	s_nop 0
	global_load_lds_dwordx4 v[200:201], off offset:2048
	v_lshl_add_u64 v[134:135], v[134:135], 0, s[40:41]
	v_lshl_add_u64 v[200:201], v[200:201], 0, s[40:41]
	s_cmpk_lt_u32 s36, 0x80
	s_cbranch_scc1 .Lat1_pre_t2
	s_mov_b32 s73, 0x10000
	s_lshl_b32 s70, s42, 4
	s_and_b32 s70, s70, 0x1c00
	s_add_i32 s73, s73, s70
	s_add_i32 m0, s73, 0x0
	s_nop 0
	global_load_lds_dwordx4 v[134:135], off
	s_add_i32 m0, s73, 0x2000
	s_nop 0
	global_load_lds_dwordx4 v[200:201], off
	s_add_i32 m0, s73, 0x7800
	s_nop 0
	global_load_lds_dwordx4 v[134:135], off offset:2048
	s_add_i32 m0, s73, 0x9800
	s_nop 0
	global_load_lds_dwordx4 v[200:201], off offset:2048
	v_lshl_add_u64 v[134:135], v[134:135], 0, s[40:41]
	v_lshl_add_u64 v[200:201], v[200:201], 0, s[40:41]
	v_mov_b32_e32 v222, 0
	v_mov_b32_e32 v223, 0
	v_mov_b32_e32 v224, 0
	v_mov_b32_e32 v225, 0
	v_mov_b32_e32 v226, 0
	v_mov_b32_e32 v227, 0
	v_mov_b32_e32 v228, 0
	v_mov_b32_e32 v229, 0
	v_mov_b32_e32 v230, 0
	v_mov_b32_e32 v231, 0
	v_mov_b32_e32 v232, 0
	v_mov_b32_e32 v233, 0
	v_mov_b32_e32 v234, 0
	v_mov_b32_e32 v235, 0
	v_mov_b32_e32 v236, 0
	v_mov_b32_e32 v237, 0
	s_waitcnt vmcnt(6)
	s_branch .Lat1_pre_done
